# test: layer-1 bf16 weight stores of the tail conversions (consumed phases later) non-temporal
# speedup vs baseline: 1.0075x; 1.0020x over previous
; #define LAS __attribute__((address_space(3)))
; __device__ __forceinline__ unsigned cvt_pk_bf16(float lo, float hi) { unsigned r; asm volatile("v_cvt_pk_bf16_f32 %0, %1, %2" : "=v"(r) : "v"(lo), "v"(hi)); return r; }
; __device__ __forceinline__ void tr_finish(const TrDesc& d, int lane, const f32x4 (&wv)[8], LAS float* scr) {
;     const int nblk = d.N / 32, kb = d.item / nblk, nb = d.item % nblk, k0 = 64 * kb, n0 = 32 * nb;
;     const int d0 = d.reorder ? (nb < 32 ? n0 : (nb < 34 ? n0 + 2048 : n0 - 64)) : n0;
; #pragma unroll
;     for (int i = 0; i < 8; ++i) { const int kk = 8 * i + (lane >> 3); f32x4 v = wv[i]; if (d.gk) v = v * d.gk[k0 + kk];
;         LAS float* p = scr + kk * 33 + (lane & 7) * 4; p[0] = v[0]; p[1] = v[1]; p[2] = v[2]; p[3] = v[3]; }
;     asm volatile("s_waitcnt lgkmcnt(0)" ::: "memory");
;     const int c = lane & 7;
; #pragma unroll
;     for (int j = 0; j < 4; ++j) { const int n = (lane >> 3) + 8 * j; const LAS float* sp = scr + (8 * c) * 33 + n;
;         u32x4 o; o.x = cvt_pk_bf16(sp[0 * 33], sp[1 * 33]); o.y = cvt_pk_bf16(sp[2 * 33], sp[3 * 33]); o.z = cvt_pk_bf16(sp[4 * 33], sp[5 * 33]); o.w = cvt_pk_bf16(sp[6 * 33], sp[7 * 33]);
;         *(u32x4*)(d.WT + (size_t)(d0 + n) * d.K + k0 + 8 * c) = o; }
;     asm volatile("s_waitcnt lgkmcnt(0)" ::: "memory");
; }
; __device__ __forceinline__ void tr_run(const Args& a, int list, int first, int stride, int lane, LAS float* scr, int n_end = -1) {
;     ...
;     for (;;) {
;         const int nit = it + stride; const bool more = nit < n;
;         TrDesc dn = d; f32x4 wn[8];
;         if (more) { dn = tr_desc(a, list, nit); tr_load(dn, lane, wn); }
;         tr_finish(d, lane, wv, scr);
;         if (!more) break;
; #pragma unroll
;         for (int i = 0; i < 8; ++i) wv[i] = wn[i];
;         d = dn; it = nit;
;     }
.LBB0_325:
	s_mul_i32 s41, s41, s40
	v_add_u32_e32 v0, 0x1ce0, v74
	s_sub_i32 s22, s38, s41
	ds_write2_b32 v0, v52, v53 offset1:1
	v_add_u32_e32 v0, 0x1ce8, v74
	s_cmp_gt_i32 s22, 31
	ds_write2_b32 v0, v54, v55 offset1:1
	s_cselect_b64 s[0:1], -1, 0
	s_waitcnt lgkmcnt(0)
	s_and_b64 s[0:1], s[18:19], s[0:1]
	ds_read2_b32 v[0:1], v73 offset1:33
	s_cmp_lt_i32 s22, 34
	s_waitcnt lgkmcnt(0)
	v_cvt_pk_bf16_f32 v0, v0, v1
	ds_read2_b32 v[2:3], v73 offset0:66 offset1:99
	s_cselect_b32 s18, 0x800, s31
	s_and_b64 s[0:1], s[0:1], exec
	s_waitcnt lgkmcnt(0)
	v_cvt_pk_bf16_f32 v1, v2, v3
	ds_read2_b32 v[2:3], v73 offset0:132 offset1:165
	s_cselect_b32 s0, s18, 0
	s_lshl_b32 s1, s22, 5
	s_waitcnt lgkmcnt(0)
	v_cvt_pk_bf16_f32 v2, v2, v3
	ds_read2_b32 v[4:5], v73 offset0:198 offset1:231
	s_add_i32 s22, s0, s1
	s_waitcnt lgkmcnt(0)
	v_cvt_pk_bf16_f32 v3, v4, v5
	v_or_b32_e32 v4, s22, v64
	v_mad_u64_u32 v[4:5], s[0:1], v4, s30, 0
	s_ashr_i32 s0, s22, 31
	s_mul_i32 s23, s0, s30
	v_add_u32_e32 v5, s23, v5
	v_lshl_add_u64 v[4:5], v[4:5], 1, s[4:5]
	s_lshl_b64 s[0:1], s[26:27], 1
	v_lshl_add_u64 v[4:5], v[4:5], 0, s[0:1]
	v_lshl_add_u64 v[4:5], v[4:5], 0, v[66:67]
	ds_read2_b32 v[6:7], v73 offset0:8 offset1:41
	global_store_dwordx4 v[4:5], v[0:3], off nt
	s_andn2_b64 vcc, exec, s[24:25]
	s_waitcnt lgkmcnt(0)
	v_cvt_pk_bf16_f32 v0, v6, v7
	ds_read2_b32 v[2:3], v73 offset0:74 offset1:107
	s_waitcnt lgkmcnt(0)
	v_cvt_pk_bf16_f32 v1, v2, v3
	ds_read2_b32 v[2:3], v73 offset0:140 offset1:173
	s_waitcnt lgkmcnt(0)
	v_cvt_pk_bf16_f32 v2, v2, v3
	ds_read2_b32 v[4:5], v73 offset0:206 offset1:239
	v_or_b32_e32 v6, s22, v70
	s_waitcnt lgkmcnt(0)
	v_cvt_pk_bf16_f32 v3, v4, v5
	v_mad_u64_u32 v[4:5], s[18:19], v6, s30, 0
	v_add_u32_e32 v5, s23, v5
	v_lshl_add_u64 v[4:5], v[4:5], 1, s[4:5]
	v_lshl_add_u64 v[4:5], v[4:5], 0, s[0:1]
	v_lshl_add_u64 v[4:5], v[4:5], 0, v[66:67]
	ds_read2_b32 v[6:7], v73 offset0:16 offset1:49
	global_store_dwordx4 v[4:5], v[0:3], off nt
	s_waitcnt lgkmcnt(0)
	s_nop 0
	v_cvt_pk_bf16_f32 v0, v6, v7
	ds_read2_b32 v[2:3], v73 offset0:82 offset1:115
	s_waitcnt lgkmcnt(0)
	v_cvt_pk_bf16_f32 v1, v2, v3
	ds_read2_b32 v[2:3], v73 offset0:148 offset1:181
	s_waitcnt lgkmcnt(0)
	v_cvt_pk_bf16_f32 v2, v2, v3
	v_or_b32_e32 v3, s22, v71
	v_mad_u64_u32 v[6:7], s[18:19], v3, s30, 0
	v_add_u32_e32 v7, s23, v7
	v_lshl_add_u64 v[6:7], v[6:7], 1, s[4:5]
	ds_read2_b32 v[4:5], v73 offset0:214 offset1:247
	v_lshl_add_u64 v[6:7], v[6:7], 0, s[0:1]
	s_waitcnt lgkmcnt(0)
	v_cvt_pk_bf16_f32 v3, v4, v5
	ds_read2_b32 v[4:5], v73 offset0:24 offset1:57
	v_lshl_add_u64 v[6:7], v[6:7], 0, v[66:67]
	global_store_dwordx4 v[6:7], v[0:3], off nt
	s_waitcnt lgkmcnt(0)
	s_nop 0
	v_cvt_pk_bf16_f32 v0, v4, v5
	v_or_b32_e32 v4, s22, v72
	v_mad_u64_u32 v[4:5], s[18:19], v4, s30, 0
	v_add_u32_e32 v5, s23, v5
	v_lshl_add_u64 v[4:5], v[4:5], 1, s[4:5]
	ds_read2_b32 v[2:3], v73 offset0:90 offset1:123
	v_lshl_add_u64 v[4:5], v[4:5], 0, s[0:1]
	s_waitcnt lgkmcnt(0)
	v_cvt_pk_bf16_f32 v1, v2, v3
	ds_read2_b32 v[2:3], v73 offset0:156 offset1:189
	v_lshl_add_u64 v[4:5], v[4:5], 0, v[66:67]
	s_waitcnt lgkmcnt(0)
	v_cvt_pk_bf16_f32 v2, v2, v3
	ds_read2_b32 v[6:7], v73 offset0:222 offset1:255
	s_waitcnt lgkmcnt(0)
	v_cvt_pk_bf16_f32 v3, v6, v7
	global_store_dwordx4 v[4:5], v[0:3], off nt
	s_waitcnt lgkmcnt(0)
	s_mov_b64 s[0:1], -1
	s_cbranch_vccnz .LBB0_305
	s_addk_i32 s34, 0x400
	s_mov_b64 s[0:1], 0
	v_mov_b32_e32 v11, v47
	v_mov_b32_e32 v10, v46
	v_mov_b32_e32 v9, v45
	v_mov_b32_e32 v8, v44
	v_mov_b32_e32 v3, v35
	v_mov_b32_e32 v2, v34
	v_mov_b32_e32 v1, v33
	v_mov_b32_e32 v0, v32
	v_mov_b32_e32 v15, v39
	v_mov_b32_e32 v14, v38
	v_mov_b32_e32 v13, v37
	v_mov_b32_e32 v12, v36
	v_mov_b32_e32 v7, v27
	v_mov_b32_e32 v6, v26
	v_mov_b32_e32 v5, v25
	v_mov_b32_e32 v4, v24
	v_mov_b32_e32 v55, v31
	v_mov_b32_e32 v54, v30
	v_mov_b32_e32 v53, v29
	v_mov_b32_e32 v52, v28
	v_mov_b32_e32 v59, v19
	v_mov_b32_e32 v58, v18
	v_mov_b32_e32 v57, v17
	v_mov_b32_e32 v56, v16
	v_mov_b32_e32 v63, v23
	v_mov_b32_e32 v62, v22
	v_mov_b32_e32 v61, v21
	v_mov_b32_e32 v60, v20
	s_branch .LBB0_305

; #define LAS __attribute__((address_space(3)))
; __device__ __forceinline__ unsigned cvt_pk_bf16(float lo, float hi) { unsigned r; asm volatile("v_cvt_pk_bf16_f32 %0, %1, %2" : "=v"(r) : "v"(lo), "v"(hi)); return r; }
; __device__ __forceinline__ void tr_finish(const TrDesc& d, int lane, const f32x4 (&wv)[8], LAS float* scr) {
;     const int nblk = d.N / 32, kb = d.item / nblk, nb = d.item % nblk, k0 = 64 * kb, n0 = 32 * nb;
;     const int d0 = d.reorder ? (nb < 32 ? n0 : (nb < 34 ? n0 + 2048 : n0 - 64)) : n0;
; #pragma unroll
;     for (int i = 0; i < 8; ++i) { const int kk = 8 * i + (lane >> 3); f32x4 v = wv[i]; if (d.gk) v = v * d.gk[k0 + kk];
;         LAS float* p = scr + kk * 33 + (lane & 7) * 4; p[0] = v[0]; p[1] = v[1]; p[2] = v[2]; p[3] = v[3]; }
;     asm volatile("s_waitcnt lgkmcnt(0)" ::: "memory");
;     const int c = lane & 7;
; #pragma unroll
;     for (int j = 0; j < 4; ++j) { const int n = (lane >> 3) + 8 * j; const LAS float* sp = scr + (8 * c) * 33 + n;
;         u32x4 o; o.x = cvt_pk_bf16(sp[0 * 33], sp[1 * 33]); o.y = cvt_pk_bf16(sp[2 * 33], sp[3 * 33]); o.z = cvt_pk_bf16(sp[4 * 33], sp[5 * 33]); o.w = cvt_pk_bf16(sp[6 * 33], sp[7 * 33]);
;         *(u32x4*)(d.WT + (size_t)(d0 + n) * d.K + k0 + 8 * c) = o; }
;     asm volatile("s_waitcnt lgkmcnt(0)" ::: "memory");
; }
; __device__ __forceinline__ void tr_run(const Args& a, int list, int first, int stride, int lane, LAS float* scr, int n_end = -1) {
;     ...
;     for (;;) {
;         const int nit = it + stride; const bool more = nit < n;
;         TrDesc dn = d; f32x4 wn[8];
;         if (more) { dn = tr_desc(a, list, nit); tr_load(dn, lane, wn); }
;         tr_finish(d, lane, wv, scr);
;         if (!more) break;
; #pragma unroll
;         for (int i = 0; i < 8; ++i) wv[i] = wn[i];
;         d = dn; it = nit;
;     }
.LBB0_655:
	s_waitcnt vmcnt(0)
	ds_write2_b32 v73, v56, v57 offset1:1
	ds_write2_b32 v73, v58, v59 offset0:2 offset1:3
	v_add_u32_e32 v56, 0x420, v73
	ds_write2_b32 v56, v44, v45 offset1:1
	v_add_u32_e32 v44, 0x428, v73
	ds_write2_b32 v44, v46, v47 offset1:1
	v_add_u32_e32 v44, 0x840, v73
	ds_write2_b32 v44, v52, v53 offset1:1
	v_add_u32_e32 v44, 0x848, v73
	ds_write2_b32 v44, v54, v55 offset1:1
	v_add_u32_e32 v44, 0xc60, v73
	ds_write2_b32 v44, v36, v37 offset1:1
	v_add_u32_e32 v36, 0xc68, v73
	ds_write2_b32 v36, v38, v39 offset1:1
	v_add_u32_e32 v36, 0x1080, v73
	ds_write2_b32 v36, v48, v49 offset1:1
	v_add_u32_e32 v36, 0x1088, v73
	ds_write2_b32 v36, v50, v51 offset1:1
	v_add_u32_e32 v36, 0x14a0, v73
	ds_write2_b32 v36, v32, v33 offset1:1
	v_add_u32_e32 v32, 0x14a8, v73
	ds_write2_b32 v32, v34, v35 offset1:1
	v_add_u32_e32 v32, 0x18c0, v73
	ds_write2_b32 v32, v40, v41 offset1:1
	v_add_u32_e32 v32, 0x18c8, v73
	ds_write2_b32 v32, v42, v43 offset1:1
	v_add_u32_e32 v32, 0x1ce0, v73
	ds_write2_b32 v32, v60, v61 offset1:1
	v_add_u32_e32 v32, 0x1ce8, v73
	ds_write2_b32 v32, v62, v63 offset1:1
	s_ashr_i32 s11, s10, 31
	s_waitcnt lgkmcnt(0)
	s_lshr_b32 s11, s11, 26
	ds_read2_b32 v[32:33], v72 offset1:33
	s_add_i32 s11, s10, s11
	s_waitcnt lgkmcnt(0)
	v_cvt_pk_bf16_f32 v32, v32, v33
	ds_read2_b32 v[34:35], v72 offset0:66 offset1:99
	s_and_b32 s22, s11, 0xffffffc0
	s_waitcnt lgkmcnt(0)
	v_cvt_pk_bf16_f32 v33, v34, v35
	ds_read2_b32 v[34:35], v72 offset0:132 offset1:165
	s_sub_i32 s10, s10, s22
	s_waitcnt lgkmcnt(0)
	v_cvt_pk_bf16_f32 v34, v34, v35
	ds_read2_b32 v[36:37], v72 offset0:198 offset1:231
	s_lshl_b32 s24, s10, 5
	s_waitcnt lgkmcnt(0)
	v_cvt_pk_bf16_f32 v35, v36, v37
	v_or_b32_e32 v36, s24, v68
	v_ashrrev_i32_e32 v37, 31, v36
	s_ashr_i32 s23, s22, 31
	v_lshlrev_b64 v[36:37], 12, v[36:37]
	v_lshl_add_u64 v[36:37], s[90:91], 0, v[36:37]
	s_lshl_b64 s[10:11], s[22:23], 1
	v_lshl_add_u64 v[36:37], v[36:37], 0, s[10:11]
	v_lshl_add_u64 v[36:37], v[36:37], 0, v[64:65]
	ds_read2_b32 v[38:39], v72 offset0:8 offset1:41
	global_store_dwordx4 v[36:37], v[32:35], off nt
	s_andn2_b64 vcc, exec, s[0:1]
	s_mov_b64 s[0:1], -1
	s_waitcnt lgkmcnt(0)
	v_cvt_pk_bf16_f32 v32, v38, v39
	ds_read2_b32 v[34:35], v72 offset0:74 offset1:107
	s_waitcnt lgkmcnt(0)
	v_cvt_pk_bf16_f32 v33, v34, v35
	ds_read2_b32 v[34:35], v72 offset0:140 offset1:173
	s_waitcnt lgkmcnt(0)
	v_cvt_pk_bf16_f32 v34, v34, v35
	ds_read2_b32 v[36:37], v72 offset0:206 offset1:239
	s_waitcnt lgkmcnt(0)
	v_cvt_pk_bf16_f32 v35, v36, v37
	v_or_b32_e32 v36, s24, v69
	v_ashrrev_i32_e32 v37, 31, v36
	v_lshlrev_b64 v[36:37], 12, v[36:37]
	v_lshl_add_u64 v[36:37], s[90:91], 0, v[36:37]
	v_lshl_add_u64 v[36:37], v[36:37], 0, s[10:11]
	v_lshl_add_u64 v[36:37], v[36:37], 0, v[64:65]
	ds_read2_b32 v[38:39], v72 offset0:16 offset1:49
	global_store_dwordx4 v[36:37], v[32:35], off nt
	s_waitcnt lgkmcnt(0)
	s_nop 0
	v_cvt_pk_bf16_f32 v32, v38, v39
	ds_read2_b32 v[34:35], v72 offset0:82 offset1:115
	s_waitcnt lgkmcnt(0)
	v_cvt_pk_bf16_f32 v33, v34, v35
	ds_read2_b32 v[34:35], v72 offset0:148 offset1:181
	s_waitcnt lgkmcnt(0)
	v_cvt_pk_bf16_f32 v34, v34, v35
	ds_read2_b32 v[36:37], v72 offset0:214 offset1:247
	s_waitcnt lgkmcnt(0)
	v_cvt_pk_bf16_f32 v35, v36, v37
	v_or_b32_e32 v36, s24, v70
	v_ashrrev_i32_e32 v37, 31, v36
	v_lshlrev_b64 v[36:37], 12, v[36:37]
	v_lshl_add_u64 v[36:37], s[90:91], 0, v[36:37]
	v_lshl_add_u64 v[36:37], v[36:37], 0, s[10:11]
	v_lshl_add_u64 v[36:37], v[36:37], 0, v[64:65]
	ds_read2_b32 v[38:39], v72 offset0:24 offset1:57
	global_store_dwordx4 v[36:37], v[32:35], off nt
	s_waitcnt lgkmcnt(0)
	s_nop 0
	v_cvt_pk_bf16_f32 v32, v38, v39
	ds_read2_b32 v[34:35], v72 offset0:90 offset1:123
	s_waitcnt lgkmcnt(0)
	v_cvt_pk_bf16_f32 v33, v34, v35
	ds_read2_b32 v[34:35], v72 offset0:156 offset1:189
	s_waitcnt lgkmcnt(0)
	v_cvt_pk_bf16_f32 v34, v34, v35
	ds_read2_b32 v[36:37], v72 offset0:222 offset1:255
	s_waitcnt lgkmcnt(0)
	v_cvt_pk_bf16_f32 v35, v36, v37
	v_or_b32_e32 v36, s24, v71
	v_ashrrev_i32_e32 v37, 31, v36
	v_lshlrev_b64 v[36:37], 12, v[36:37]
	v_lshl_add_u64 v[36:37], s[90:91], 0, v[36:37]
	v_lshl_add_u64 v[36:37], v[36:37], 0, s[10:11]
	v_lshl_add_u64 v[36:37], v[36:37], 0, v[64:65]
	global_store_dwordx4 v[36:37], v[32:35], off nt
	s_waitcnt lgkmcnt(0)
	s_cbranch_vccnz .LBB0_652
	s_addk_i32 s7, 0x6000
	s_mov_b64 s[0:1], 0
	v_mov_b32_e32 v43, v31
	v_mov_b32_e32 v42, v30
	v_mov_b32_e32 v41, v29
	v_mov_b32_e32 v40, v28
	v_mov_b32_e32 v35, v19
	v_mov_b32_e32 v34, v18
	v_mov_b32_e32 v33, v17
	v_mov_b32_e32 v32, v16
	v_mov_b32_e32 v51, v23
	v_mov_b32_e32 v50, v22
	v_mov_b32_e32 v49, v21
	v_mov_b32_e32 v48, v20
	v_mov_b32_e32 v39, v11
	v_mov_b32_e32 v38, v10
	v_mov_b32_e32 v37, v9
	v_mov_b32_e32 v36, v8
	v_mov_b32_e32 v55, v15
	v_mov_b32_e32 v54, v14
	v_mov_b32_e32 v53, v13
	v_mov_b32_e32 v52, v12
	v_mov_b32_e32 v47, v3
	v_mov_b32_e32 v46, v2
	v_mov_b32_e32 v45, v1
	v_mov_b32_e32 v44, v0
	v_mov_b32_e32 v59, v7
	v_mov_b32_e32 v58, v6
	v_mov_b32_e32 v57, v5
	v_mov_b32_e32 v56, v4
	s_branch .LBB0_652
